# prep: weight convert/transpose rewritten per wave (private LDS tile per wave, no workgroup barriers, 8 tiles in flight per CU)
# speedup vs baseline: 1.0027x; 1.0027x over previous
; __device__ __forceinline__ uint2 pack4(float a, float b, float c, float d) { uint2 r; r.x = pk2(a, b); r.y = pk2(c, d); return r; }
; __device__ __forceinline__ void prep_phase(const Params& p, KArgsP kap, char* shm, int wv) {
;     ...
;   for (int t = bid; t < kap->total_wtiles; t += G) {
;     int wi = 0;
;     while (wi + 1 < kap->nwd && kap->wd[wi + 1].tile0 <= t) ++wi;
;     const float* src = kap->wd[wi].src; u16* dst = kap->wd[wi].dst; const float* gain = kap->wd[wi].gain;
;     int K = kap->wd[wi].K, N = kap->wd[wi].N, perm = kap->wd[wi].perm;
;     int lt = t - kap->wd[wi].tile0, nNt = N >> 6;
;     int k0 = (lt / nNt) * 64, n0 = (lt % nNt) * 64;
;     {
;       int kk = tid >> 3, seg = (tid & 7) * 8;
;       const float4* s4 = (const float4*)(src + (long)(k0 + kk) * N + n0 + seg);
;       float4 a = s4[0], b = s4[1]; float g = gain ? gain[k0 + kk] : 1.f;
;       float* d = tl + kk * 65 + seg;
;       d[0] = a.x * g; d[1] = a.y * g; d[2] = a.z * g; d[3] = a.w * g; d[4] = b.x * g; d[5] = b.y * g; d[6] = b.z * g; d[7] = b.w * g;
;     }
;     __syncthreads();
;     {
;       int nn = tid >> 3, seg = (tid & 7) * 8;
;       int n = n0 + nn, drow = n;
;       if (perm) { int part = n / DFF, idx = n % DFF; drow = (idx >> 7) * 256 + part * 128 + (idx & 127); }
;       float v[8]; _Pragma("unroll") for (int i = 0; i < 8; ++i) v[i] = tl[(seg + i) * 65 + nn];
;       uint4 o; uint2 lo = pack4(v[0], v[1], v[2], v[3]), hi = pack4(v[4], v[5], v[6], v[7]);
;       o.x = lo.x; o.y = lo.y; o.z = hi.x; o.w = hi.y;
;       *(uint4*)&dst[(long)drow * K + k0 + seg] = o;
;     }
;     __syncthreads();
;   }
.LBB0_24:
.Lw_entry:
	s_mov_b64 exec, -1
	s_load_dword s24, s[2:3], 0x4e8
	v_mbcnt_lo_u32_b32 v2, -1, 0
	v_mbcnt_hi_u32_b32 v2, -1, v2
	v_lshrrev_b32_e32 v3, 4, v2
	v_and_b32_e32 v4, 15, v2
	v_lshlrev_b32_e32 v4, 2, v4
	s_mul_i32 s27, s97, 260
	v_mul_u32_u24_e32 v5, 65, v3
	v_add_u32_e32 v5, v5, v4
	v_lshl_add_u32 v5, v5, 2, s27
	v_and_b32_e32 v11, 7, v2
	v_mul_u32_u24_e32 v11, 520, v11
	v_lshrrev_b32_e32 v12, 3, v2
	v_add_u32_e32 v6, v11, v12
	v_lshl_add_u32 v6, v6, 2, s27
	v_add_u32_e32 v7, 0x410, v6
	s_lshr_b32 s27, s97, 6
	s_mul_i32 s27, s27, s70
	s_add_i32 s21, s72, s27
	s_lshl_b32 s22, s70, 3
	s_mov_b32 s23, 0
	s_waitcnt lgkmcnt(0)
	s_cmp_ge_i32 s21, s20
	s_cbranch_scc1 .Lw_done
.Lw_tile:
.Lw_search:
	s_add_i32 s25, s23, 1
	s_cmp_ge_i32 s25, s24
	s_cbranch_scc1 .Lw_found
	s_mul_i32 s26, s23, 40
	s_add_i32 s26, s26, 0xd4
	s_load_dword s27, s[2:3], s26
	s_waitcnt lgkmcnt(0)
	s_cmp_gt_i32 s27, s21
	s_cbranch_scc1 .Lw_found
	s_mov_b32 s23, s25
	s_branch .Lw_search
.Lw_found:
	s_mul_i32 s26, s23, 40
	s_add_i32 s26, s26, 0x88
	s_load_dwordx8 s[8:15], s[2:3], s26
	s_add_i32 s26, s26, 32
	s_load_dwordx2 s[16:17], s[2:3], s26
	s_waitcnt lgkmcnt(0)
	s_sub_i32 s28, s21, s17
	s_lshr_b32 s29, s15, 6
	v_cvt_f32_u32_e32 v11, s29
	v_rcp_iflag_f32_e32 v11, v11
	v_cvt_f32_u32_e32 v12, s28
	v_mul_f32_e32 v11, v12, v11
	v_cvt_u32_f32_e32 v11, v11
	s_nop 0
	v_readfirstlane_b32 s30, v11
	s_nop 3
	s_mul_i32 s27, s30, s29
	s_sub_i32 s31, s28, s27
	s_cmp_lt_i32 s31, 0
	s_cbranch_scc0 .Lw_fix1
	s_sub_i32 s30, s30, 1
	s_add_i32 s31, s31, s29
.Lw_fix1:
	s_cmp_ge_i32 s31, s29
	s_cbranch_scc0 .Lw_fix2
	s_add_i32 s30, s30, 1
	s_sub_i32 s31, s31, s29
.Lw_fix2:
	s_lshl_b32 s32, s30, 6
	s_lshl_b32 s33, s31, 6
	s_mul_i32 s34, s32, s15
	s_add_i32 s34, s34, s33
	s_lshl_b32 s34, s34, 2
	s_lshl_b32 s27, s15, 2
	v_mul_lo_u32 v8, v3, s27
	v_lshl_add_u32 v8, v4, 2, v8
	v_add_u32_e32 v8, s34, v8
	s_lshl_b32 s35, s15, 4
	s_cmp_eq_u64 s[12:13], 0
	s_cbranch_scc1 .Lw_nogain
	v_and_b32_e32 v10, 7, v2
	v_lshlrev_b32_e32 v10, 5, v10
	s_lshl_b32 s27, s32, 2
	v_add_u32_e32 v10, s27, v10
	global_load_dwordx4 v[80:83], v10, s[12:13]
	global_load_dwordx4 v[84:87], v10, s[12:13] offset:16
	s_branch .Lw_gdone
.Lw_nogain:
	v_mov_b32_e32 v80, 1.0
	v_mov_b32_e32 v81, 1.0
	v_mov_b32_e32 v82, 1.0
	v_mov_b32_e32 v83, 1.0
	v_mov_b32_e32 v84, 1.0
	v_mov_b32_e32 v85, 1.0
	v_mov_b32_e32 v86, 1.0
	v_mov_b32_e32 v87, 1.0
.Lw_gdone:
	global_load_dwordx4 v[16:19], v8, s[8:9]
	v_add_u32_e32 v8, s35, v8
	global_load_dwordx4 v[20:23], v8, s[8:9]
	v_add_u32_e32 v8, s35, v8
	global_load_dwordx4 v[24:27], v8, s[8:9]
	v_add_u32_e32 v8, s35, v8
	global_load_dwordx4 v[28:31], v8, s[8:9]
	v_add_u32_e32 v8, s35, v8
	global_load_dwordx4 v[32:35], v8, s[8:9]
	v_add_u32_e32 v8, s35, v8
	global_load_dwordx4 v[36:39], v8, s[8:9]
	v_add_u32_e32 v8, s35, v8
	global_load_dwordx4 v[40:43], v8, s[8:9]
	v_add_u32_e32 v8, s35, v8
	global_load_dwordx4 v[44:47], v8, s[8:9]
	v_add_u32_e32 v8, s35, v8
	global_load_dwordx4 v[48:51], v8, s[8:9]
	v_add_u32_e32 v8, s35, v8
	global_load_dwordx4 v[52:55], v8, s[8:9]
	v_add_u32_e32 v8, s35, v8
	global_load_dwordx4 v[56:59], v8, s[8:9]
	v_add_u32_e32 v8, s35, v8
	global_load_dwordx4 v[60:63], v8, s[8:9]
	v_add_u32_e32 v8, s35, v8
	global_load_dwordx4 v[64:67], v8, s[8:9]
	v_add_u32_e32 v8, s35, v8
	global_load_dwordx4 v[68:71], v8, s[8:9]
	v_add_u32_e32 v8, s35, v8
	global_load_dwordx4 v[72:75], v8, s[8:9]
	v_add_u32_e32 v8, s35, v8
	global_load_dwordx4 v[76:79], v8, s[8:9]
	s_mov_b32 s38, s33
	s_cmp_eq_u32 s16, 0
	s_cbranch_scc1 .Lw_noperm
	s_cmp_ge_u32 s33, 0xb00
	s_cselect_b32 s27, 0xb00, 0
	s_cselect_b32 s25, 0x80, 0
	s_sub_i32 s27, s33, s27
	s_lshr_b32 s38, s27, 7
	s_lshl_b32 s38, s38, 8
	s_and_b32 s27, s27, 0x7f
	s_add_i32 s38, s38, s27
	s_add_i32 s38, s38, s25
.Lw_noperm:
	s_mul_i32 s36, s38, s14
	s_add_i32 s36, s36, s32
	s_lshl_b32 s36, s36, 1
	v_lshrrev_b32_e32 v11, 3, v2
	v_mul_lo_u32 v11, v11, s14
	v_and_b32_e32 v12, 7, v2
	v_lshl_add_u32 v11, v12, 3, v11
	v_lshl_add_u32 v9, v11, 1, s36
	s_lshl_b32 s37, s14, 4
	s_waitcnt vmcnt(15)
	ds_write_b32 v5, v16 offset:0
	ds_write_b32 v5, v17 offset:4
	ds_write_b32 v5, v18 offset:8
	ds_write_b32 v5, v19 offset:12
	s_waitcnt vmcnt(14)
	ds_write_b32 v5, v20 offset:1040
	ds_write_b32 v5, v21 offset:1044
	ds_write_b32 v5, v22 offset:1048
	ds_write_b32 v5, v23 offset:1052
	s_waitcnt vmcnt(13)
	ds_write_b32 v5, v24 offset:2080
	ds_write_b32 v5, v25 offset:2084
	ds_write_b32 v5, v26 offset:2088
	ds_write_b32 v5, v27 offset:2092
	s_waitcnt vmcnt(12)
	ds_write_b32 v5, v28 offset:3120
	ds_write_b32 v5, v29 offset:3124
	ds_write_b32 v5, v30 offset:3128
	ds_write_b32 v5, v31 offset:3132
	s_waitcnt vmcnt(11)
	ds_write_b32 v5, v32 offset:4160
	ds_write_b32 v5, v33 offset:4164
	ds_write_b32 v5, v34 offset:4168
	ds_write_b32 v5, v35 offset:4172
	s_waitcnt vmcnt(10)
	ds_write_b32 v5, v36 offset:5200
	ds_write_b32 v5, v37 offset:5204
	ds_write_b32 v5, v38 offset:5208
	ds_write_b32 v5, v39 offset:5212
	s_waitcnt vmcnt(9)
	ds_write_b32 v5, v40 offset:6240
	ds_write_b32 v5, v41 offset:6244
	ds_write_b32 v5, v42 offset:6248
	ds_write_b32 v5, v43 offset:6252
	s_waitcnt vmcnt(8)
	ds_write_b32 v5, v44 offset:7280
	ds_write_b32 v5, v45 offset:7284
	ds_write_b32 v5, v46 offset:7288
	ds_write_b32 v5, v47 offset:7292
	s_waitcnt vmcnt(7)
	ds_write_b32 v5, v48 offset:8320
	ds_write_b32 v5, v49 offset:8324
	ds_write_b32 v5, v50 offset:8328
	ds_write_b32 v5, v51 offset:8332
	s_waitcnt vmcnt(6)
	ds_write_b32 v5, v52 offset:9360
	ds_write_b32 v5, v53 offset:9364
	ds_write_b32 v5, v54 offset:9368
	ds_write_b32 v5, v55 offset:9372
	s_waitcnt vmcnt(5)
; __device__ __forceinline__ uint2 pack4(float a, float b, float c, float d) { uint2 r; r.x = pk2(a, b); r.y = pk2(c, d); return r; }
; __device__ __forceinline__ void prep_phase(const Params& p, KArgsP kap, char* shm, int wv) {
;     ...
;       float* d = tl + kk * 65 + seg;
;       d[0] = a.x * g; d[1] = a.y * g; d[2] = a.z * g; d[3] = a.w * g; d[4] = b.x * g; d[5] = b.y * g; d[6] = b.z * g; d[7] = b.w * g;
;     }
;     __syncthreads();
;     {
;       int nn = tid >> 3, seg = (tid & 7) * 8;
;       int n = n0 + nn, drow = n;
;       if (perm) { int part = n / DFF, idx = n % DFF; drow = (idx >> 7) * 256 + part * 128 + (idx & 127); }
;       float v[8]; _Pragma("unroll") for (int i = 0; i < 8; ++i) v[i] = tl[(seg + i) * 65 + nn];
;       uint4 o; uint2 lo = pack4(v[0], v[1], v[2], v[3]), hi = pack4(v[4], v[5], v[6], v[7]);
;       o.x = lo.x; o.y = lo.y; o.z = hi.x; o.w = hi.y;
;       *(uint4*)&dst[(long)drow * K + k0 + seg] = o;
;     }
;     __syncthreads();
	ds_write_b32 v5, v56 offset:10400
	ds_write_b32 v5, v57 offset:10404
	ds_write_b32 v5, v58 offset:10408
	ds_write_b32 v5, v59 offset:10412
	s_waitcnt vmcnt(4)
	ds_write_b32 v5, v60 offset:11440
	ds_write_b32 v5, v61 offset:11444
	ds_write_b32 v5, v62 offset:11448
	ds_write_b32 v5, v63 offset:11452
	s_waitcnt vmcnt(3)
	ds_write_b32 v5, v64 offset:12480
	ds_write_b32 v5, v65 offset:12484
	ds_write_b32 v5, v66 offset:12488
	ds_write_b32 v5, v67 offset:12492
	s_waitcnt vmcnt(2)
	ds_write_b32 v5, v68 offset:13520
	ds_write_b32 v5, v69 offset:13524
	ds_write_b32 v5, v70 offset:13528
	ds_write_b32 v5, v71 offset:13532
	s_waitcnt vmcnt(1)
	ds_write_b32 v5, v72 offset:14560
	ds_write_b32 v5, v73 offset:14564
	ds_write_b32 v5, v74 offset:14568
	ds_write_b32 v5, v75 offset:14572
	s_waitcnt vmcnt(0)
	ds_write_b32 v5, v76 offset:15600
	ds_write_b32 v5, v77 offset:15604
	ds_write_b32 v5, v78 offset:15608
	ds_write_b32 v5, v79 offset:15612
	s_waitcnt lgkmcnt(0)
	ds_read2_b32 v[88:89], v6 offset0:0 offset1:65
	ds_read2_b32 v[90:91], v6 offset0:130 offset1:195
	ds_read2_b32 v[92:93], v7 offset0:0 offset1:65
	ds_read2_b32 v[94:95], v7 offset0:130 offset1:195
	s_waitcnt lgkmcnt(0)
	v_mul_f32_e32 v88, v88, v80
	v_mul_f32_e32 v89, v89, v81
	v_mul_f32_e32 v90, v90, v82
	v_mul_f32_e32 v91, v91, v83
	v_mul_f32_e32 v92, v92, v84
	v_mul_f32_e32 v93, v93, v85
	v_mul_f32_e32 v94, v94, v86
	v_mul_f32_e32 v95, v95, v87
	v_cvt_pk_bf16_f32 v96, v88, v89
	v_cvt_pk_bf16_f32 v97, v90, v91
	v_cvt_pk_bf16_f32 v98, v92, v93
	v_cvt_pk_bf16_f32 v99, v94, v95
	global_store_dwordx4 v9, v[96:99], s[10:11]
	v_add_u32_e32 v9, s37, v9
	s_nop 1
	ds_read2_b32 v[88:89], v6 offset0:8 offset1:73
	ds_read2_b32 v[90:91], v6 offset0:138 offset1:203
	ds_read2_b32 v[92:93], v7 offset0:8 offset1:73
	ds_read2_b32 v[94:95], v7 offset0:138 offset1:203
	s_waitcnt lgkmcnt(0)
	v_mul_f32_e32 v88, v88, v80
	v_mul_f32_e32 v89, v89, v81
	v_mul_f32_e32 v90, v90, v82
	v_mul_f32_e32 v91, v91, v83
	v_mul_f32_e32 v92, v92, v84
	v_mul_f32_e32 v93, v93, v85
	v_mul_f32_e32 v94, v94, v86
	v_mul_f32_e32 v95, v95, v87
	v_cvt_pk_bf16_f32 v96, v88, v89
	v_cvt_pk_bf16_f32 v97, v90, v91
	v_cvt_pk_bf16_f32 v98, v92, v93
	v_cvt_pk_bf16_f32 v99, v94, v95
	global_store_dwordx4 v9, v[96:99], s[10:11]
	v_add_u32_e32 v9, s37, v9
	s_nop 1
	ds_read2_b32 v[88:89], v6 offset0:16 offset1:81
	ds_read2_b32 v[90:91], v6 offset0:146 offset1:211
	ds_read2_b32 v[92:93], v7 offset0:16 offset1:81
	ds_read2_b32 v[94:95], v7 offset0:146 offset1:211
	s_waitcnt lgkmcnt(0)
	v_mul_f32_e32 v88, v88, v80
	v_mul_f32_e32 v89, v89, v81
	v_mul_f32_e32 v90, v90, v82
	v_mul_f32_e32 v91, v91, v83
	v_mul_f32_e32 v92, v92, v84
	v_mul_f32_e32 v93, v93, v85
	v_mul_f32_e32 v94, v94, v86
	v_mul_f32_e32 v95, v95, v87
	v_cvt_pk_bf16_f32 v96, v88, v89
	v_cvt_pk_bf16_f32 v97, v90, v91
	v_cvt_pk_bf16_f32 v98, v92, v93
	v_cvt_pk_bf16_f32 v99, v94, v95
	global_store_dwordx4 v9, v[96:99], s[10:11]
	v_add_u32_e32 v9, s37, v9
	s_nop 1
	ds_read2_b32 v[88:89], v6 offset0:24 offset1:89
	ds_read2_b32 v[90:91], v6 offset0:154 offset1:219
	ds_read2_b32 v[92:93], v7 offset0:24 offset1:89
	ds_read2_b32 v[94:95], v7 offset0:154 offset1:219
	s_waitcnt lgkmcnt(0)
	v_mul_f32_e32 v88, v88, v80
	v_mul_f32_e32 v89, v89, v81
	v_mul_f32_e32 v90, v90, v82
	v_mul_f32_e32 v91, v91, v83
	v_mul_f32_e32 v92, v92, v84
	v_mul_f32_e32 v93, v93, v85
	v_mul_f32_e32 v94, v94, v86
	v_mul_f32_e32 v95, v95, v87
	v_cvt_pk_bf16_f32 v96, v88, v89
	v_cvt_pk_bf16_f32 v97, v90, v91
	v_cvt_pk_bf16_f32 v98, v92, v93
	v_cvt_pk_bf16_f32 v99, v94, v95
	global_store_dwordx4 v9, v[96:99], s[10:11]
	v_add_u32_e32 v9, s37, v9
	s_nop 1
	ds_read2_b32 v[88:89], v6 offset0:32 offset1:97
	ds_read2_b32 v[90:91], v6 offset0:162 offset1:227
	ds_read2_b32 v[92:93], v7 offset0:32 offset1:97
	ds_read2_b32 v[94:95], v7 offset0:162 offset1:227
	s_waitcnt lgkmcnt(0)
	v_mul_f32_e32 v88, v88, v80
	v_mul_f32_e32 v89, v89, v81
	v_mul_f32_e32 v90, v90, v82
	v_mul_f32_e32 v91, v91, v83
	v_mul_f32_e32 v92, v92, v84
	v_mul_f32_e32 v93, v93, v85
	v_mul_f32_e32 v94, v94, v86
	v_mul_f32_e32 v95, v95, v87
	v_cvt_pk_bf16_f32 v96, v88, v89
	v_cvt_pk_bf16_f32 v97, v90, v91
	v_cvt_pk_bf16_f32 v98, v92, v93
	v_cvt_pk_bf16_f32 v99, v94, v95
	global_store_dwordx4 v9, v[96:99], s[10:11]
	v_add_u32_e32 v9, s37, v9
	s_nop 1
	ds_read2_b32 v[88:89], v6 offset0:40 offset1:105
	ds_read2_b32 v[90:91], v6 offset0:170 offset1:235
	ds_read2_b32 v[92:93], v7 offset0:40 offset1:105
	ds_read2_b32 v[94:95], v7 offset0:170 offset1:235
	s_waitcnt lgkmcnt(0)
	v_mul_f32_e32 v88, v88, v80
	v_mul_f32_e32 v89, v89, v81
	v_mul_f32_e32 v90, v90, v82
	v_mul_f32_e32 v91, v91, v83
	v_mul_f32_e32 v92, v92, v84
	v_mul_f32_e32 v93, v93, v85
	v_mul_f32_e32 v94, v94, v86
	v_mul_f32_e32 v95, v95, v87
	v_cvt_pk_bf16_f32 v96, v88, v89
	v_cvt_pk_bf16_f32 v97, v90, v91
	v_cvt_pk_bf16_f32 v98, v92, v93
	v_cvt_pk_bf16_f32 v99, v94, v95
	global_store_dwordx4 v9, v[96:99], s[10:11]
	v_add_u32_e32 v9, s37, v9
	s_nop 1
	ds_read2_b32 v[88:89], v6 offset0:48 offset1:113
	ds_read2_b32 v[90:91], v6 offset0:178 offset1:243
	ds_read2_b32 v[92:93], v7 offset0:48 offset1:113
	ds_read2_b32 v[94:95], v7 offset0:178 offset1:243
	s_waitcnt lgkmcnt(0)
	v_mul_f32_e32 v88, v88, v80
	v_mul_f32_e32 v89, v89, v81
	v_mul_f32_e32 v90, v90, v82
	v_mul_f32_e32 v91, v91, v83
	v_mul_f32_e32 v92, v92, v84
	v_mul_f32_e32 v93, v93, v85
	v_mul_f32_e32 v94, v94, v86
	v_mul_f32_e32 v95, v95, v87
	v_cvt_pk_bf16_f32 v96, v88, v89
	v_cvt_pk_bf16_f32 v97, v90, v91
	v_cvt_pk_bf16_f32 v98, v92, v93
	v_cvt_pk_bf16_f32 v99, v94, v95
	global_store_dwordx4 v9, v[96:99], s[10:11]
	v_add_u32_e32 v9, s37, v9
	s_nop 1
	ds_read2_b32 v[88:89], v6 offset0:56 offset1:121
	ds_read2_b32 v[90:91], v6 offset0:186 offset1:251
	ds_read2_b32 v[92:93], v7 offset0:56 offset1:121
	ds_read2_b32 v[94:95], v7 offset0:186 offset1:251
	s_waitcnt lgkmcnt(0)
	v_mul_f32_e32 v88, v88, v80
	v_mul_f32_e32 v89, v89, v81
	v_mul_f32_e32 v90, v90, v82
	v_mul_f32_e32 v91, v91, v83
	v_mul_f32_e32 v92, v92, v84
	v_mul_f32_e32 v93, v93, v85
	v_mul_f32_e32 v94, v94, v86
	v_mul_f32_e32 v95, v95, v87
	v_cvt_pk_bf16_f32 v96, v88, v89
	v_cvt_pk_bf16_f32 v97, v90, v91
	v_cvt_pk_bf16_f32 v98, v92, v93
	v_cvt_pk_bf16_f32 v99, v94, v95
	global_store_dwordx4 v9, v[96:99], s[10:11]
	s_nop 1
	s_add_i32 s21, s21, s22
	s_cmp_lt_i32 s21, s20
	s_cbranch_scc1 .Lw_tile
.Lw_done:
	s_waitcnt vmcnt(0)
	s_branch .LBB0_35
